# v081 + tile-boundary barrier re-pairing in the W_in GEMM instance as well
# baseline (speedup 1.0000x reference)
.LBB0_1113:
	s_add_i32 s85, s76, -2
	s_add_u32 s64, s64, 0x80
	s_addc_u32 s65, s65, 0
	s_add_u32 s91, s66, 0x100
	v_mov_b64_e32 v[0:1], 0
	v_mov_b64_e32 v[2:3], 0
	v_mov_b64_e32 v[4:5], 0
	v_mov_b64_e32 v[6:7], 0
	v_mov_b64_e32 v[8:9], 0
	v_mov_b64_e32 v[10:11], 0
	v_mov_b64_e32 v[12:13], 0
	v_mov_b64_e32 v[14:15], 0
	v_mov_b64_e32 v[16:17], 0
	v_mov_b64_e32 v[18:19], 0
	v_mov_b64_e32 v[20:21], 0
	v_mov_b64_e32 v[22:23], 0
	v_mov_b64_e32 v[24:25], 0
	v_mov_b64_e32 v[26:27], 0
	v_mov_b64_e32 v[28:29], 0
	v_mov_b64_e32 v[30:31], 0
	v_mov_b64_e32 v[32:33], 0
	v_mov_b64_e32 v[34:35], 0
	v_mov_b64_e32 v[36:37], 0
	v_mov_b64_e32 v[38:39], 0
	v_mov_b64_e32 v[40:41], 0
	v_mov_b64_e32 v[42:43], 0
	v_mov_b64_e32 v[44:45], 0
	v_mov_b64_e32 v[46:47], 0
	v_mov_b64_e32 v[48:49], 0
	v_mov_b64_e32 v[50:51], 0
	v_mov_b64_e32 v[52:53], 0
	v_mov_b64_e32 v[54:55], 0
	v_mov_b64_e32 v[56:57], 0
	v_mov_b64_e32 v[58:59], 0
	v_mov_b64_e32 v[60:61], 0
	v_mov_b64_e32 v[62:63], 0
	v_mov_b64_e32 v[64:65], 0
	v_mov_b64_e32 v[66:67], 0
	v_mov_b64_e32 v[68:69], 0
	v_mov_b64_e32 v[70:71], 0
	v_mov_b64_e32 v[72:73], 0
	v_mov_b64_e32 v[74:75], 0
	v_mov_b64_e32 v[76:77], 0
	v_mov_b64_e32 v[78:79], 0
	v_mov_b64_e32 v[80:81], 0
	v_mov_b64_e32 v[82:83], 0
	v_mov_b64_e32 v[84:85], 0
	v_mov_b64_e32 v[86:87], 0
	v_mov_b64_e32 v[88:89], 0
	v_mov_b64_e32 v[90:91], 0
	v_mov_b64_e32 v[92:93], 0
	v_mov_b64_e32 v[94:95], 0
	v_mov_b64_e32 v[96:97], 0
	v_mov_b64_e32 v[98:99], 0
	v_mov_b64_e32 v[100:101], 0
	v_mov_b64_e32 v[102:103], 0
	v_mov_b64_e32 v[104:105], 0
	v_mov_b64_e32 v[106:107], 0
	v_mov_b64_e32 v[108:109], 0
	v_mov_b64_e32 v[110:111], 0
	v_mov_b64_e32 v[112:113], 0
	v_mov_b64_e32 v[114:115], 0
	v_mov_b64_e32 v[116:117], 0
	v_mov_b64_e32 v[118:119], 0
	v_mov_b64_e32 v[120:121], 0
	v_mov_b64_e32 v[122:123], 0
	v_mov_b64_e32 v[124:125], 0
	v_mov_b64_e32 v[126:127], 0
	s_addc_u32 vcc_lo, s67, 0
	s_mov_b32 s66, 0
	v_add_u32_e32 v174, 0x10000, v194
	s_cmpk_gt_u32 s37, 0xff
	s_cbranch_scc0 .Ltb_win_e2_skip
	s_cmp_gt_u32 s59, 1
	s_cbranch_scc0 .Ltb_win_e2_skip
	s_barrier

.LBB0_1114:
	s_add_i32 vcc_hi, s66, 2
	s_add_u32 s28, s64, 0x80
	s_addc_u32 s29, s65, 0
	s_add_i32 s88, 0, 0x10000
	ds_read_b128 v[128:131], v174
	ds_read_b128 v[132:135], v174 offset:1024
	ds_read_b128 v[136:139], v174 offset:2048
	ds_read_b128 v[140:143], v174 offset:3072
	s_cmp_eq_u32 s85, s66
	s_cselect_b32 s66, s4, s28
	s_cselect_b32 s67, s5, s29
	s_cselect_b32 s69, s7, vcc_lo
	s_cselect_b32 s68, s6, s91
	s_add_i32 m0, s70, 0xc000
	ds_read_b128 v[144:147], v195
	ds_read_b128 v[162:165], v195 offset:2048
	ds_read_b128 v[170:173], v195 offset:4096
	ds_read_b128 v[196:199], v195 offset:6144
	ds_read_b128 v[148:151], v195 offset:1024
	ds_read_b128 v[166:169], v195 offset:3072
	ds_read_b128 v[188:191], v195 offset:5120
	ds_read_b128 v[200:203], v195 offset:7168
	global_load_lds_dwordx4 v158, s[64:65]
	s_add_i32 m0, s70, 0xe000
	s_nop 0
	global_load_lds_dwordx4 v160, s[64:65]
	s_waitcnt lgkmcnt(8)
	s_barrier
	s_waitcnt lgkmcnt(7)
	v_mfma_f32_16x16x32_bf16 v[124:127], v[128:131], v[144:147], v[124:127]
	v_mfma_f32_16x16x32_bf16 v[120:123], v[136:139], v[144:147], v[120:123]
	s_waitcnt lgkmcnt(6)
	v_mfma_f32_16x16x32_bf16 v[108:111], v[128:131], v[162:165], v[108:111]
	v_mfma_f32_16x16x32_bf16 v[104:107], v[136:139], v[162:165], v[104:107]
	s_waitcnt lgkmcnt(5)
	v_mfma_f32_16x16x32_bf16 v[92:95], v[128:131], v[170:173], v[92:95]
	v_mfma_f32_16x16x32_bf16 v[88:91], v[136:139], v[170:173], v[88:91]
	s_waitcnt lgkmcnt(4)
	v_mfma_f32_16x16x32_bf16 v[76:79], v[128:131], v[196:199], v[76:79]
	v_mfma_f32_16x16x32_bf16 v[72:75], v[136:139], v[196:199], v[72:75]
	s_waitcnt lgkmcnt(3)
	v_mfma_f32_16x16x32_bf16 v[124:127], v[132:135], v[148:151], v[124:127]
	v_mfma_f32_16x16x32_bf16 v[120:123], v[140:143], v[148:151], v[120:123]
	s_waitcnt lgkmcnt(2)
	v_mfma_f32_16x16x32_bf16 v[108:111], v[132:135], v[166:169], v[108:111]
	v_mfma_f32_16x16x32_bf16 v[104:107], v[140:143], v[166:169], v[104:107]
	s_waitcnt lgkmcnt(1)
	v_mfma_f32_16x16x32_bf16 v[92:95], v[132:135], v[188:191], v[92:95]
	v_mfma_f32_16x16x32_bf16 v[88:91], v[140:143], v[188:191], v[88:91]
	s_waitcnt lgkmcnt(0)
	v_mfma_f32_16x16x32_bf16 v[76:79], v[132:135], v[200:203], v[76:79]
	v_mfma_f32_16x16x32_bf16 v[72:75], v[140:143], v[200:203], v[72:75]
	s_barrier
	s_add_i32 s28, 0, 0x14000
	s_add_i32 s29, s88, s47
	ds_read_b128 v[204:207], v174 offset:16384
	ds_read_b128 v[208:211], v174 offset:17408
	ds_read_b128 v[212:215], v174 offset:18432
	ds_read_b128 v[232:235], v174 offset:19456
	s_mov_b32 m0, s29
	s_nop 0
	global_load_lds_dwordx4 v176, s[68:69]
	s_add_i32 m0, s29, 0x2000
	s_nop 0
	global_load_lds_dwordx4 v156, s[68:69]
	s_barrier
	s_waitcnt lgkmcnt(3)
	v_mfma_f32_16x16x32_bf16 v[116:119], v[204:207], v[144:147], v[116:119]
	s_waitcnt lgkmcnt(1)
	v_mfma_f32_16x16x32_bf16 v[112:115], v[212:215], v[144:147], v[112:115]
	v_mfma_f32_16x16x32_bf16 v[100:103], v[204:207], v[162:165], v[100:103]
	v_mfma_f32_16x16x32_bf16 v[96:99], v[212:215], v[162:165], v[96:99]
	v_mfma_f32_16x16x32_bf16 v[84:87], v[204:207], v[170:173], v[84:87]
	v_mfma_f32_16x16x32_bf16 v[80:83], v[212:215], v[170:173], v[80:83]
	v_mfma_f32_16x16x32_bf16 v[68:71], v[204:207], v[196:199], v[68:71]
	v_mfma_f32_16x16x32_bf16 v[64:67], v[212:215], v[196:199], v[64:67]
	v_mfma_f32_16x16x32_bf16 v[116:119], v[208:211], v[148:151], v[116:119]
	s_waitcnt lgkmcnt(0)
	v_mfma_f32_16x16x32_bf16 v[112:115], v[232:235], v[148:151], v[112:115]
	v_mfma_f32_16x16x32_bf16 v[100:103], v[208:211], v[166:169], v[100:103]
	v_mfma_f32_16x16x32_bf16 v[96:99], v[232:235], v[166:169], v[96:99]
	v_mfma_f32_16x16x32_bf16 v[84:87], v[208:211], v[188:191], v[84:87]
	v_mfma_f32_16x16x32_bf16 v[80:83], v[232:235], v[188:191], v[80:83]
	v_mfma_f32_16x16x32_bf16 v[68:71], v[208:211], v[200:203], v[68:71]
	v_mfma_f32_16x16x32_bf16 v[64:67], v[232:235], v[200:203], v[64:67]
	s_mov_b32 m0, s70
	s_barrier
	ds_read_b128 v[144:147], v195 offset:16384
	ds_read_b128 v[162:165], v195 offset:18432
	ds_read_b128 v[170:173], v195 offset:20480
	ds_read_b128 v[196:199], v195 offset:22528
	ds_read_b128 v[148:151], v195 offset:17408
	ds_read_b128 v[166:169], v195 offset:19456
	ds_read_b128 v[188:191], v195 offset:21504
	ds_read_b128 v[200:203], v195 offset:23552
	global_load_lds_dwordx4 v152, s[66:67]
	s_mov_b32 m0, s71
	s_nop 0
	global_load_lds_dwordx4 v154, s[66:67]
	s_barrier
	s_waitcnt lgkmcnt(7)
	v_mfma_f32_16x16x32_bf16 v[60:63], v[128:131], v[144:147], v[60:63]
	v_mfma_f32_16x16x32_bf16 v[56:59], v[136:139], v[144:147], v[56:59]
	s_waitcnt lgkmcnt(6)
	v_mfma_f32_16x16x32_bf16 v[44:47], v[128:131], v[162:165], v[44:47]
	v_mfma_f32_16x16x32_bf16 v[40:43], v[136:139], v[162:165], v[40:43]
	s_waitcnt lgkmcnt(5)
	v_mfma_f32_16x16x32_bf16 v[28:31], v[128:131], v[170:173], v[28:31]
	v_mfma_f32_16x16x32_bf16 v[24:27], v[136:139], v[170:173], v[24:27]
	s_waitcnt lgkmcnt(4)
	v_mfma_f32_16x16x32_bf16 v[12:15], v[128:131], v[196:199], v[12:15]
	v_mfma_f32_16x16x32_bf16 v[8:11], v[136:139], v[196:199], v[8:11]
	s_waitcnt lgkmcnt(3)
	v_mfma_f32_16x16x32_bf16 v[60:63], v[132:135], v[148:151], v[60:63]
	v_mfma_f32_16x16x32_bf16 v[56:59], v[140:143], v[148:151], v[56:59]
	s_waitcnt lgkmcnt(2)
	v_mfma_f32_16x16x32_bf16 v[44:47], v[132:135], v[166:169], v[44:47]
	v_mfma_f32_16x16x32_bf16 v[40:43], v[140:143], v[166:169], v[40:43]
	s_waitcnt lgkmcnt(1)
	v_mfma_f32_16x16x32_bf16 v[28:31], v[132:135], v[188:191], v[28:31]
	v_mfma_f32_16x16x32_bf16 v[24:27], v[140:143], v[188:191], v[24:27]
	s_waitcnt lgkmcnt(0)
	v_mfma_f32_16x16x32_bf16 v[12:15], v[132:135], v[200:203], v[12:15]
	v_mfma_f32_16x16x32_bf16 v[8:11], v[140:143], v[200:203], v[8:11]
	s_barrier
	s_add_u32 s98, s68, s58
	s_addc_u32 s99, s69, 0
	s_add_i32 s28, s28, s47
	s_mov_b32 m0, s28
	s_nop 0
	global_load_lds_dwordx4 v176, s[98:99]
	s_add_i32 m0, s28, 0x2000
	s_nop 0
	global_load_lds_dwordx4 v156, s[98:99]
	s_waitcnt vmcnt(6)
	s_barrier
	v_mfma_f32_16x16x32_bf16 v[52:55], v[204:207], v[144:147], v[52:55]
	v_mfma_f32_16x16x32_bf16 v[48:51], v[212:215], v[144:147], v[48:51]
	v_mfma_f32_16x16x32_bf16 v[36:39], v[204:207], v[162:165], v[36:39]
	v_mfma_f32_16x16x32_bf16 v[32:35], v[212:215], v[162:165], v[32:35]
	v_mfma_f32_16x16x32_bf16 v[20:23], v[204:207], v[170:173], v[20:23]
	v_mfma_f32_16x16x32_bf16 v[16:19], v[212:215], v[170:173], v[16:19]
	v_mfma_f32_16x16x32_bf16 v[4:7], v[204:207], v[196:199], v[4:7]
	v_mfma_f32_16x16x32_bf16 v[0:3], v[212:215], v[196:199], v[0:3]
	v_mfma_f32_16x16x32_bf16 v[52:55], v[208:211], v[148:151], v[52:55]
	v_mfma_f32_16x16x32_bf16 v[48:51], v[232:235], v[148:151], v[48:51]
	v_mfma_f32_16x16x32_bf16 v[36:39], v[208:211], v[166:169], v[36:39]
	v_mfma_f32_16x16x32_bf16 v[32:35], v[232:235], v[166:169], v[32:35]
	v_mfma_f32_16x16x32_bf16 v[20:23], v[208:211], v[188:191], v[20:23]
	v_mfma_f32_16x16x32_bf16 v[16:19], v[232:235], v[188:191], v[16:19]
	v_mfma_f32_16x16x32_bf16 v[4:7], v[208:211], v[200:203], v[4:7]
	v_mfma_f32_16x16x32_bf16 v[0:3], v[232:235], v[200:203], v[0:3]
	s_add_i32 s28, 0, 0x18000
	s_barrier
	ds_read_b128 v[128:131], v174 offset:32768
	ds_read_b128 v[132:135], v174 offset:33792
	ds_read_b128 v[136:139], v174 offset:34816
	ds_read_b128 v[140:143], v174 offset:35840
	s_add_u32 s100, s66, s58
	s_addc_u32 s101, s67, 0
	s_mov_b32 m0, s72
	ds_read_b128 v[144:147], v195 offset:32768
	ds_read_b128 v[162:165], v195 offset:34816
	ds_read_b128 v[170:173], v195 offset:36864
	ds_read_b128 v[196:199], v195 offset:38912
	ds_read_b128 v[148:151], v195 offset:33792
	ds_read_b128 v[166:169], v195 offset:35840
	ds_read_b128 v[188:191], v195 offset:37888
	ds_read_b128 v[200:203], v195 offset:39936
	global_load_lds_dwordx4 v152, s[100:101]
	s_mov_b32 m0, s73
	s_nop 0
	global_load_lds_dwordx4 v154, s[100:101]
	s_waitcnt lgkmcnt(8)
	s_barrier
	s_waitcnt lgkmcnt(7)
	v_mfma_f32_16x16x32_bf16 v[124:127], v[128:131], v[144:147], v[124:127]
	v_mfma_f32_16x16x32_bf16 v[120:123], v[136:139], v[144:147], v[120:123]
	s_waitcnt lgkmcnt(6)
	v_mfma_f32_16x16x32_bf16 v[108:111], v[128:131], v[162:165], v[108:111]
	v_mfma_f32_16x16x32_bf16 v[104:107], v[136:139], v[162:165], v[104:107]
	s_waitcnt lgkmcnt(5)
	v_mfma_f32_16x16x32_bf16 v[92:95], v[128:131], v[170:173], v[92:95]
	v_mfma_f32_16x16x32_bf16 v[88:91], v[136:139], v[170:173], v[88:91]
	s_waitcnt lgkmcnt(4)
	v_mfma_f32_16x16x32_bf16 v[76:79], v[128:131], v[196:199], v[76:79]
	v_mfma_f32_16x16x32_bf16 v[72:75], v[136:139], v[196:199], v[72:75]
	s_waitcnt lgkmcnt(3)
	v_mfma_f32_16x16x32_bf16 v[124:127], v[132:135], v[148:151], v[124:127]
	v_mfma_f32_16x16x32_bf16 v[120:123], v[140:143], v[148:151], v[120:123]
	s_waitcnt lgkmcnt(2)
	v_mfma_f32_16x16x32_bf16 v[108:111], v[132:135], v[166:169], v[108:111]
	v_mfma_f32_16x16x32_bf16 v[104:107], v[140:143], v[166:169], v[104:107]
	s_waitcnt lgkmcnt(1)
	v_mfma_f32_16x16x32_bf16 v[92:95], v[132:135], v[188:191], v[92:95]
	v_mfma_f32_16x16x32_bf16 v[88:91], v[140:143], v[188:191], v[88:91]
	s_waitcnt lgkmcnt(0)
	v_mfma_f32_16x16x32_bf16 v[76:79], v[132:135], v[200:203], v[76:79]
	v_mfma_f32_16x16x32_bf16 v[72:75], v[140:143], v[200:203], v[72:75]
	s_barrier
	s_add_i32 s29, 0, 0x1c000
	s_add_i32 s28, s28, s47
	s_add_i32 m0, s28, 0xffffff80
	ds_read_b128 v[204:207], v174 offset:49152
	ds_read_b128 v[208:211], v174 offset:50176
	ds_read_b128 v[212:215], v174 offset:51200
	ds_read_b128 v[232:235], v174 offset:52224
	global_load_lds_dwordx4 v176, s[68:69] offset:128
	s_add_i32 m0, s28, 0x1f80
	s_nop 0
	global_load_lds_dwordx4 v156, s[68:69] offset:128
	s_barrier
	s_waitcnt lgkmcnt(3)
	v_mfma_f32_16x16x32_bf16 v[116:119], v[204:207], v[144:147], v[116:119]
	s_waitcnt lgkmcnt(1)
	v_mfma_f32_16x16x32_bf16 v[112:115], v[212:215], v[144:147], v[112:115]
	v_mfma_f32_16x16x32_bf16 v[100:103], v[204:207], v[162:165], v[100:103]
	v_mfma_f32_16x16x32_bf16 v[96:99], v[212:215], v[162:165], v[96:99]
	v_mfma_f32_16x16x32_bf16 v[84:87], v[204:207], v[170:173], v[84:87]
	v_mfma_f32_16x16x32_bf16 v[80:83], v[212:215], v[170:173], v[80:83]
	v_mfma_f32_16x16x32_bf16 v[68:71], v[204:207], v[196:199], v[68:71]
	v_mfma_f32_16x16x32_bf16 v[64:67], v[212:215], v[196:199], v[64:67]
	v_mfma_f32_16x16x32_bf16 v[116:119], v[208:211], v[148:151], v[116:119]
	s_waitcnt lgkmcnt(0)
	v_mfma_f32_16x16x32_bf16 v[112:115], v[232:235], v[148:151], v[112:115]
	v_mfma_f32_16x16x32_bf16 v[100:103], v[208:211], v[166:169], v[100:103]
	v_mfma_f32_16x16x32_bf16 v[96:99], v[232:235], v[166:169], v[96:99]
	v_mfma_f32_16x16x32_bf16 v[84:87], v[208:211], v[188:191], v[84:87]
	v_mfma_f32_16x16x32_bf16 v[80:83], v[232:235], v[188:191], v[80:83]
	v_mfma_f32_16x16x32_bf16 v[68:71], v[208:211], v[200:203], v[68:71]
	v_mfma_f32_16x16x32_bf16 v[64:67], v[232:235], v[200:203], v[64:67]
	s_add_i32 m0, s74, 0xffffff80
	s_barrier
	ds_read_b128 v[144:147], v195 offset:49152
	ds_read_b128 v[162:165], v195 offset:51200
	ds_read_b128 v[170:173], v195 offset:53248
	ds_read_b128 v[196:199], v195 offset:55296
	ds_read_b128 v[148:151], v195 offset:50176
	ds_read_b128 v[166:169], v195 offset:52224
	ds_read_b128 v[188:191], v195 offset:54272
	ds_read_b128 v[200:203], v195 offset:56320
	global_load_lds_dwordx4 v152, s[66:67] offset:128
	s_add_i32 m0, s75, 0xffffff80
	s_nop 0
	global_load_lds_dwordx4 v154, s[66:67] offset:128
	s_barrier
	s_waitcnt lgkmcnt(7)
	v_mfma_f32_16x16x32_bf16 v[60:63], v[128:131], v[144:147], v[60:63]
	v_mfma_f32_16x16x32_bf16 v[56:59], v[136:139], v[144:147], v[56:59]
	s_waitcnt lgkmcnt(6)
	v_mfma_f32_16x16x32_bf16 v[44:47], v[128:131], v[162:165], v[44:47]
	v_mfma_f32_16x16x32_bf16 v[40:43], v[136:139], v[162:165], v[40:43]
	s_waitcnt lgkmcnt(5)
	v_mfma_f32_16x16x32_bf16 v[28:31], v[128:131], v[170:173], v[28:31]
	v_mfma_f32_16x16x32_bf16 v[24:27], v[136:139], v[170:173], v[24:27]
	s_waitcnt lgkmcnt(4)
	v_mfma_f32_16x16x32_bf16 v[12:15], v[128:131], v[196:199], v[12:15]
	v_mfma_f32_16x16x32_bf16 v[8:11], v[136:139], v[196:199], v[8:11]
	s_waitcnt lgkmcnt(3)
	v_mfma_f32_16x16x32_bf16 v[60:63], v[132:135], v[148:151], v[60:63]
	v_mfma_f32_16x16x32_bf16 v[56:59], v[140:143], v[148:151], v[56:59]
	s_waitcnt lgkmcnt(2)
	v_mfma_f32_16x16x32_bf16 v[44:47], v[132:135], v[166:169], v[44:47]
	v_mfma_f32_16x16x32_bf16 v[40:43], v[140:143], v[166:169], v[40:43]
	s_waitcnt lgkmcnt(1)
	v_mfma_f32_16x16x32_bf16 v[28:31], v[132:135], v[188:191], v[28:31]
	v_mfma_f32_16x16x32_bf16 v[24:27], v[140:143], v[188:191], v[24:27]
	s_waitcnt lgkmcnt(0)
	v_mfma_f32_16x16x32_bf16 v[12:15], v[132:135], v[200:203], v[12:15]
	v_mfma_f32_16x16x32_bf16 v[8:11], v[140:143], v[200:203], v[8:11]
	s_barrier
	s_add_i32 s28, s29, s47
	s_add_i32 m0, s28, 0xffffff80
	s_nop 0
	global_load_lds_dwordx4 v176, s[98:99] offset:128
	s_add_i32 m0, s28, 0x1f80
	s_nop 0
	global_load_lds_dwordx4 v156, s[98:99] offset:128
	s_waitcnt vmcnt(6)
	s_barrier
	v_mfma_f32_16x16x32_bf16 v[52:55], v[204:207], v[144:147], v[52:55]
	v_mfma_f32_16x16x32_bf16 v[48:51], v[212:215], v[144:147], v[48:51]
	v_mfma_f32_16x16x32_bf16 v[36:39], v[204:207], v[162:165], v[36:39]
	v_mfma_f32_16x16x32_bf16 v[32:35], v[212:215], v[162:165], v[32:35]
	v_mfma_f32_16x16x32_bf16 v[20:23], v[204:207], v[170:173], v[20:23]
	v_mfma_f32_16x16x32_bf16 v[16:19], v[212:215], v[170:173], v[16:19]
	v_mfma_f32_16x16x32_bf16 v[4:7], v[204:207], v[196:199], v[4:7]
	v_mfma_f32_16x16x32_bf16 v[0:3], v[212:215], v[196:199], v[0:3]
	v_mfma_f32_16x16x32_bf16 v[52:55], v[208:211], v[148:151], v[52:55]
	v_mfma_f32_16x16x32_bf16 v[48:51], v[232:235], v[148:151], v[48:51]
	v_mfma_f32_16x16x32_bf16 v[36:39], v[208:211], v[166:169], v[36:39]
	v_mfma_f32_16x16x32_bf16 v[32:35], v[232:235], v[166:169], v[32:35]
	v_mfma_f32_16x16x32_bf16 v[20:23], v[208:211], v[188:191], v[20:23]
	v_mfma_f32_16x16x32_bf16 v[16:19], v[232:235], v[188:191], v[16:19]
	v_mfma_f32_16x16x32_bf16 v[4:7], v[208:211], v[200:203], v[4:7]
	v_mfma_f32_16x16x32_bf16 v[0:3], v[232:235], v[200:203], v[0:3]
	s_add_u32 s64, s64, 0x100
	s_addc_u32 s65, s65, 0
	s_add_u32 s91, s91, 0x100
	s_addc_u32 vcc_lo, vcc_lo, 0
	s_cmp_lt_i32 vcc_hi, s76
	s_mov_b32 s66, vcc_hi
	s_barrier
	s_cbranch_scc1 .LBB0_1114
	s_cmpk_gt_u32 s37, 0xff
	s_cbranch_scc1 .Ltb_win_e1_skip
	s_barrier
.Ltb_win_e1_skip:
	s_lshl_b32 s28, s84, 8
	v_mov_b32_e32 v128, v193
	v_mov_b32_e32 v129, v192
	s_add_i32 s28, s28, s78
	s_lshl_b32 s64, s24, 2
	v_add_u32_e32 v166, s28, v129
	s_lshl_b32 s28, s24, 8
	s_or_b32 s28, s28, s79
	v_lshl_add_u32 v162, v128, 3, s28
	v_ashrrev_i32_e32 v163, 31, v162
	v_lshlrev_b64 v[204:205], 1, v[162:163]
	v_ashrrev_i32_e32 v167, 31, v166
	v_lshl_add_u64 v[164:165], s[12:13], 0, v[204:205]
	v_lshlrev_b64 v[206:207], 11, v[166:167]
	v_cmp_eq_u32_e32 vcc, 0, v128
	v_lshl_add_u64 v[128:129], v[164:165], 0, v[206:207]
	global_load_dwordx4 v[196:199], v[128:129], off
	global_load_dwordx4 v[200:203], v[128:129], off offset:256
	v_add_u32_e32 v188, 16, v166
	v_ashrrev_i32_e32 v189, 31, v188
	v_add_u32_e32 v172, 32, v166
	v_lshlrev_b64 v[190:191], 11, v[188:189]
	v_ashrrev_i32_e32 v173, 31, v172
	v_add_u32_e32 v168, 48, v166
	v_lshl_add_u64 v[128:129], v[164:165], 0, v[190:191]
	v_lshlrev_b64 v[174:175], 11, v[172:173]
	v_ashrrev_i32_e32 v169, 31, v168
	global_load_dwordx4 v[148:151], v[128:129], off
	global_load_dwordx4 v[144:147], v[128:129], off offset:256
	v_lshl_add_u64 v[128:129], v[164:165], 0, v[174:175]
	v_lshlrev_b64 v[170:171], 11, v[168:169]
	global_load_dwordx4 v[140:143], v[128:129], off
	global_load_dwordx4 v[136:139], v[128:129], off offset:256
	v_lshl_add_u64 v[128:129], v[164:165], 0, v[170:171]
	global_load_dwordx4 v[132:135], v[128:129], off
	s_nop 0
	global_load_dwordx4 v[128:131], v[128:129], off offset:256
	v_lshl_add_u64 v[206:207], s[12:13], 0, v[206:207]
	v_lshl_add_u64 v[204:205], v[206:207], 0, v[204:205]
	s_ashr_i32 s65, s64, 31
	s_waitcnt vmcnt(0)
	v_lshlrev_b32_e32 v208, 16, v196
	v_and_b32_e32 v209, 0xffff0000, v196
	v_lshlrev_b32_e32 v196, 16, v197
	v_and_b32_e32 v197, 0xffff0000, v197
	v_lshlrev_b32_e32 v210, 16, v198
	v_and_b32_e32 v211, 0xffff0000, v198
	v_lshlrev_b32_e32 v198, 16, v199
	v_and_b32_e32 v199, 0xffff0000, v199
	v_pk_fma_f32 v[126:127], s[62:63], v[126:127], v[196:197]
	v_pk_fma_f32 v[124:125], s[10:11], v[124:125], v[208:209]
	v_pk_fma_f32 v[196:197], s[62:63], v[122:123], v[198:199]
	v_pk_fma_f32 v[198:199], s[10:11], v[120:121], v[210:211]
	v_cvt_pk_bf16_f32 v120, v124, v125
	v_cvt_pk_bf16_f32 v121, v126, v127
	s_nop 0
	v_cvt_pk_bf16_f32 v122, v198, v199
	v_cvt_pk_bf16_f32 v123, v196, v197
	global_store_dwordx4 v[204:205], v[120:123], off
	s_nop 1
	v_pk_mul_f32 v[120:121], v[198:199], v[198:199]
	v_pk_mul_f32 v[122:123], v[196:197], v[196:197]
	v_pk_fma_f32 v[120:121], v[124:125], v[124:125], v[120:121]
	v_pk_fma_f32 v[122:123], v[126:127], v[126:127], v[122:123]
	v_add_f32_e32 v120, v120, v121
	v_add_f32_e32 v121, v122, v123
	v_add_f32_e32 v196, v120, v121
	v_lshlrev_b32_e32 v120, 16, v200
	v_and_b32_e32 v121, 0xffff0000, v200
	v_lshlrev_b32_e32 v122, 16, v201
	v_and_b32_e32 v123, 0xffff0000, v201
	v_lshlrev_b32_e32 v124, 16, v202
	v_and_b32_e32 v125, 0xffff0000, v202
	v_lshlrev_b32_e32 v126, 16, v203
	v_and_b32_e32 v127, 0xffff0000, v203
	v_pk_fma_f32 v[118:119], s[62:63], v[118:119], v[122:123]
	v_pk_fma_f32 v[116:117], s[10:11], v[116:117], v[120:121]
	v_pk_fma_f32 v[120:121], s[62:63], v[114:115], v[126:127]
	v_pk_fma_f32 v[122:123], s[10:11], v[112:113], v[124:125]
	v_cvt_pk_bf16_f32 v112, v116, v117
	v_cvt_pk_bf16_f32 v113, v118, v119
	s_nop 0
	v_cvt_pk_bf16_f32 v114, v122, v123
	v_cvt_pk_bf16_f32 v115, v120, v121
	global_store_dwordx4 v[204:205], v[112:115], off offset:256
	s_nop 1
	v_pk_mul_f32 v[112:113], v[122:123], v[122:123]
	v_pk_mul_f32 v[114:115], v[120:121], v[120:121]
	v_pk_fma_f32 v[112:113], v[116:117], v[116:117], v[112:113]
	v_pk_fma_f32 v[114:115], v[118:119], v[118:119], v[114:115]
	v_add_f32_e32 v112, v112, v113
	v_add_f32_e32 v113, v114, v115
	v_add_f32_e32 v112, v112, v113
	v_add_f32_e32 v112, v196, v112
	v_mov_b32_e32 v113, v112
	s_waitcnt lgkmcnt(0)
	s_nop 0
	v_permlane16_swap_b32 v112, v113
	v_add_f32_e32 v112, v112, v113
	v_mov_b32_e32 v113, v112
	s_nop 1
	v_permlane32_swap_b32 v112, v113
	s_and_saveexec_b64 s[66:67], vcc
	s_cbranch_execz .LBB0_1117
	v_lshlrev_b64 v[114:115], 6, v[166:167]
	v_lshl_add_u64 v[114:115], s[8:9], 0, v[114:115]
	v_lshl_add_u64 v[114:115], s[64:65], 2, v[114:115]
	s_lshl_b32 s24, s77, 2
	v_lshl_add_u64 v[114:115], v[114:115], 0, s[24:25]
	s_waitcnt lgkmcnt(0)
	v_add_f32_e32 v112, v112, v113
	global_store_dword v[114:115], v112, off

.LBB0_1131:
	s_waitcnt vmcnt(0)
	s_cmpk_gt_u32 s37, 0xff
	s_mov_b64 s[74:75], 0x118400
	s_mov_b64 s[76:77], 0x4000
	s_movk_i32 s78, 0x4500
	s_movk_i32 s79, 0x104
	s_cbranch_scc1 .LBB0_1133
.LBB0_1133:
	s_barrier
